# stack10: + rope loop gain reloads removed and 16-lane sums via DPP
# speedup vs baseline: 1.0070x; 1.0028x over previous
; __global__ void __launch_bounds__(512, 2) fwd_mega(Args args) {
;     ...
;             int idx0 = gw;
;             for (; idx0 + 3 * NGW < TOK * 4; idx0 += 4 * NGW) {
;                 PREP_LOAD(0, idx0); PREP_LOAD(1, idx0 + NGW); PREP_LOAD(2, idx0 + 2 * NGW); PREP_LOAD(3, idx0 + 3 * NGW);
;                 PREP_ONE(p0, a0, b0, cs0, sn0, hh0); PREP_ONE(p1, a1, b1, cs1, sn1, hh1); PREP_ONE(p2, a2, b2, cs2, sn2, hh2); PREP_ONE(p3, a3, b3, cs3, sn3, hh3);
.LBB0_137:
	s_ashr_i32 s16, s0, 2
	s_add_i32 s22, s90, s0
	s_and_b32 s23, s42, 12
	s_mul_i32 s14, s16, 0x3000
	v_or_b32_e32 v0, s23, v33
	s_mul_hi_i32 s15, s16, 0x3000
	s_add_u32 s14, s38, s14
	s_addc_u32 s15, s39, s15
	v_lshlrev_b32_e32 v152, 8, v0
	v_lshl_add_u64 v[0:1], s[14:15], 0, v[152:153]
	v_lshlrev_b32_e32 v2, 1, v32
	v_mov_b32_e32 v3, v153
	s_waitcnt vmcnt(1)
	v_lshl_add_u64 v[58:59], v[0:1], 0, v[2:3]
	global_load_dwordx2 v[60:61], v[58:59], off
	global_load_dwordx2 v[62:63], v[58:59], off offset:128
	s_lshl_b32 s14, s16, 8
	s_add_i32 s16, s0, s33
	s_ashr_i32 s17, s16, 2
	s_and_b32 s26, s14, 0x7ff00
	s_mul_i32 s14, s17, 0x3000
	v_lshl_add_u64 v[0:1], v[36:37], 0, s[26:27]
	s_mul_hi_i32 s15, s17, 0x3000
	s_add_u32 s14, s38, s14
	global_load_dwordx4 v[24:27], v[0:1], off
	v_lshl_add_u64 v[0:1], v[38:39], 0, s[26:27]
	s_addc_u32 s15, s39, s15
	s_add_i32 s0, s96, s0
	global_load_dwordx4 v[28:31], v[0:1], off
	v_lshl_add_u64 v[0:1], s[14:15], 0, v[152:153]
	s_lshl_b32 s14, s17, 8
	s_ashr_i32 s0, s0, 2
	s_and_b32 s26, s14, 0x7ff00
	s_add_i32 s14, s16, s33
	s_mul_i32 s16, s0, 0x3000
	s_mul_hi_i32 s15, s0, 0x3000
	s_add_u32 s16, s38, s16
	v_lshl_add_u64 v[52:53], v[0:1], 0, v[2:3]
	v_lshl_add_u64 v[0:1], v[36:37], 0, s[26:27]
	s_addc_u32 s17, s39, s15
	s_lshl_b32 s0, s0, 8
	global_load_dwordx2 v[54:55], v[52:53], off
	global_load_dwordx2 v[56:57], v[52:53], off offset:128
	global_load_dwordx4 v[16:19], v[0:1], off
	v_lshl_add_u64 v[0:1], v[38:39], 0, s[26:27]
	s_and_b32 s26, s0, 0x7ff00
	s_ashr_i32 s0, s22, 2
	global_load_dwordx4 v[20:23], v[0:1], off
	v_lshl_add_u64 v[0:1], s[16:17], 0, v[152:153]
	s_mul_i32 s16, s0, 0x3000
	s_mul_hi_i32 s15, s0, 0x3000
	s_add_u32 s16, s38, s16
	s_waitcnt vmcnt(8)
	v_lshl_add_u64 v[46:47], v[0:1], 0, v[2:3]
	v_lshl_add_u64 v[0:1], v[36:37], 0, s[26:27]
	s_addc_u32 s17, s39, s15
	s_lshl_b32 s0, s0, 8
	global_load_dwordx2 v[48:49], v[46:47], off
	global_load_dwordx2 v[50:51], v[46:47], off offset:128
	global_load_dwordx4 v[8:11], v[0:1], off
	v_lshl_add_u64 v[0:1], v[38:39], 0, s[26:27]
	s_and_b32 s26, s0, 0x7ff00
	s_cmp_lt_u32 s23, 8
	s_cselect_b64 vcc, -1, 0
	global_load_dwordx4 v[12:15], v[0:1], off
	v_lshl_add_u64 v[0:1], s[16:17], 0, v[152:153]
	s_and_b64 s[16:17], vcc, exec
	v_lshl_add_u64 v[40:41], v[0:1], 0, v[2:3]
	v_lshl_add_u64 v[0:1], v[36:37], 0, s[26:27]
	v_lshl_add_u64 v[4:5], v[38:39], 0, s[26:27]
	s_cselect_b32 s25, s36, s40
	s_cselect_b32 s24, s37, s41
	v_lshlrev_b32_e32 v94, 2, v32
	global_load_dwordx2 v[42:43], v[40:41], off
	global_load_dwordx2 v[44:45], v[40:41], off offset:128
	v_cndmask_b32_e32 v67, 1.0, v181, vcc
	global_load_dwordx4 v[0:3], v[0:1], off
	s_add_i32 s0, s14, s96
	global_load_dwordx4 v[4:7], v[4:5], off
	s_nop 0
	global_load_dwordx4 v[68:71], v94, s[24:25]
	global_load_dwordx4 v[72:75], v94, s[24:25] offset:256
	s_add_i32 s14, s90, s0
	s_add_i32 s42, s42, s91
	s_cmpk_gt_i32 s14, 0x7fff
	s_waitcnt vmcnt(17)
	v_lshlrev_b32_e32 v77, 16, v61
	s_waitcnt vmcnt(16)
	v_lshlrev_b32_e32 v76, 16, v63
	v_and_b32_e32 v82, 0xffff0000, v63
	v_and_b32_e32 v83, 0xffff0000, v61
	v_mov_b32_e32 v86, v76
	v_mov_b32_e32 v87, v82
	v_mov_b32_e32 v84, v77
	v_mov_b32_e32 v85, v83
	v_pk_mul_f32 v[86:87], v[86:87], v[86:87]
	v_and_b32_e32 v61, 0xffff0000, v60
	v_pk_fma_f32 v[84:85], v[84:85], v[84:85], v[86:87]
	v_lshlrev_b32_e32 v87, 16, v60
	v_lshlrev_b32_e32 v86, 16, v62
	v_and_b32_e32 v60, 0xffff0000, v62
	v_mov_b32_e32 v92, v86
	v_mov_b32_e32 v93, v60
	v_mov_b32_e32 v62, v87
	v_mov_b32_e32 v63, v61
	v_pk_mul_f32 v[92:93], v[92:93], v[92:93]
	s_waitcnt vmcnt(15)
	v_mov_b32_e32 v90, v24
	v_pk_fma_f32 v[62:63], v[62:63], v[62:63], v[92:93]
	s_waitcnt vmcnt(14)
	v_mov_b32_e32 v91, v28
	v_add_f32_e32 v62, v62, v63
	v_add_f32_e32 v62, v62, v84
	v_add_f32_e32 v62, v62, v85
	v_mov_b32_e32 v80, v26
	v_mov_b32_e32 v81, v30
	s_nop 1
	v_add_f32_dpp v62, v62, v62 quad_perm:[1,0,3,2] row_mask:0xf bank_mask:0xf
	s_nop 1
	v_add_f32_dpp v62, v62, v62 quad_perm:[2,3,0,1] row_mask:0xf bank_mask:0xf
	s_nop 1
	v_add_f32_dpp v62, v62, v62 row_half_mirror row_mask:0xf bank_mask:0xf
	s_nop 1
	v_add_f32_dpp v62, v62, v62 row_mirror row_mask:0xf bank_mask:0xf
	v_fmamk_f32 v62, v62, 0x3c000000, v177
	v_rsq_f32_e32 v62, v62
	s_waitcnt vmcnt(1)
	v_mov_b32_e32 v89, v68
	s_waitcnt vmcnt(0)
; __global__ void __launch_bounds__(512, 2) fwd_mega(Args args) {
;     ...
;             int idx0 = gw;
;             for (; idx0 + 3 * NGW < TOK * 4; idx0 += 4 * NGW) {
;                 PREP_LOAD(0, idx0); PREP_LOAD(1, idx0 + NGW); PREP_LOAD(2, idx0 + 2 * NGW); PREP_LOAD(3, idx0 + 3 * NGW);
;                 PREP_ONE(p0, a0, b0, cs0, sn0, hh0); PREP_ONE(p1, a1, b1, cs1, sn1, hh1); PREP_ONE(p2, a2, b2, cs2, sn2, hh2); PREP_ONE(p3, a3, b3, cs3, sn3, hh3);
	v_mov_b32_e32 v96, v68
	v_mov_b32_e32 v97, v69
	v_mov_b32_e32 v98, v70
	v_mov_b32_e32 v99, v71
	v_mov_b32_e32 v100, v72
	v_mov_b32_e32 v101, v73
	v_mov_b32_e32 v102, v74
	v_mov_b32_e32 v103, v75
	v_mov_b32_e32 v88, v72
	v_pk_mul_f32 v[84:85], v[62:63], v[86:87] op_sel_hi:[0,1]
	v_pk_mul_f32 v[84:85], v[88:89], v[84:85]
	v_mov_b32_e32 v86, v28
	v_mov_b32_e32 v87, v24
	v_pk_mul_f32 v[86:87], v[86:87], v[84:85]
	v_pk_mul_f32 v[84:85], v[90:91], v[84:85]
	v_sub_f32_e32 v24, v87, v86
	v_mul_f32_e32 v63, v67, v24
	v_add_f32_e32 v24, v84, v85
	v_pk_mul_f32 v[60:61], v[62:63], v[60:61] op_sel_hi:[0,1]
	v_mov_b32_e32 v68, v73
	v_mul_f32_e32 v72, v67, v24
	v_pk_mul_f32 v[60:61], v[68:69], v[60:61]
	v_mov_b32_e32 v24, v29
	v_pk_mul_f32 v[68:69], v[24:25], v[60:61]
	v_mov_b32_e32 v28, v25
	v_sub_f32_e32 v24, v69, v68
	v_mul_f32_e32 v68, v67, v24
	v_pk_mul_f32 v[24:25], v[28:29], v[60:61]
	v_mov_b32_e32 v78, v74
	v_add_f32_e32 v24, v24, v25
	v_mov_b32_e32 v79, v70
	v_mul_f32_e32 v60, v67, v24
	v_pk_mul_f32 v[24:25], v[62:63], v[76:77] op_sel_hi:[0,1]
	v_pk_mul_f32 v[24:25], v[78:79], v[24:25]
	v_mov_b32_e32 v28, v30
	v_mov_b32_e32 v29, v26
	v_pk_mul_f32 v[28:29], v[28:29], v[24:25]
	v_pk_mul_f32 v[24:25], v[80:81], v[24:25]
	v_sub_f32_e32 v26, v29, v28
	v_add_f32_e32 v24, v24, v25
	v_mul_f32_e32 v69, v67, v24
	v_pk_mul_f32 v[24:25], v[62:63], v[82:83] op_sel_hi:[0,1]
	v_mov_b32_e32 v70, v75
	v_mul_f32_e32 v61, v67, v26
	v_pk_mul_f32 v[24:25], v[70:71], v[24:25]
	v_mov_b32_e32 v26, v31
	v_mov_b32_e32 v30, v27
	v_pk_mul_f32 v[28:29], v[26:27], v[24:25]
	v_pk_mul_f32 v[24:25], v[30:31], v[24:25]
	v_sub_f32_e32 v26, v29, v28
	v_add_f32_e32 v24, v24, v25
	v_mul_f32_e32 v26, v67, v26
	v_mul_f32_e32 v27, v67, v24
	v_cvt_pk_bf16_f32 v24, v63, v68
	v_cvt_pk_bf16_f32 v25, v61, v26
	v_cvt_pk_bf16_f32 v26, v72, v60
	v_cvt_pk_bf16_f32 v27, v69, v27
	global_store_dwordx2 v[58:59], v[24:25], off
	global_store_dwordx2 v[58:59], v[26:27], off offset:128
	v_mov_b32_e32 v24, v96
	v_mov_b32_e32 v25, v97
	v_mov_b32_e32 v26, v98
	v_mov_b32_e32 v27, v99
	s_nop 0
	v_mov_b32_e32 v28, v100
	v_mov_b32_e32 v29, v101
	v_mov_b32_e32 v30, v102
	v_mov_b32_e32 v31, v103
	v_lshlrev_b32_e32 v58, 16, v57
	v_and_b32_e32 v68, 0xffff0000, v57
	v_lshlrev_b32_e32 v59, 16, v55
	v_and_b32_e32 v69, 0xffff0000, v55
	v_mov_b32_e32 v72, v58
	v_mov_b32_e32 v73, v68
	v_mov_b32_e32 v70, v59
	v_mov_b32_e32 v71, v69
	v_pk_mul_f32 v[72:73], v[72:73], v[72:73]
	v_and_b32_e32 v55, 0xffff0000, v54
	v_pk_fma_f32 v[70:71], v[70:71], v[70:71], v[72:73]
	v_lshlrev_b32_e32 v73, 16, v54
	v_lshlrev_b32_e32 v72, 16, v56
	v_and_b32_e32 v54, 0xffff0000, v56
	v_mov_b32_e32 v78, v72
	v_mov_b32_e32 v79, v54
	v_mov_b32_e32 v56, v73
	v_mov_b32_e32 v57, v55
	v_pk_mul_f32 v[78:79], v[78:79], v[78:79]
	v_mov_b32_e32 v76, v16
	v_pk_fma_f32 v[56:57], v[56:57], v[56:57], v[78:79]
	v_mov_b32_e32 v77, v20
	v_mov_b32_e32 v62, v18
	v_mov_b32_e32 v63, v22
	v_mov_b32_e32 v75, v24
	v_add_f32_e32 v24, v56, v57
	v_add_f32_e32 v24, v24, v70
	v_add_f32_e32 v24, v24, v71
	v_mov_b32_e32 v61, v26
	v_mov_b32_e32 v74, v28
	v_mov_b32_e32 v70, v20
	v_mov_b32_e32 v71, v16
	v_mov_b32_e32 v60, v30
	s_nop 1
	v_add_f32_dpp v24, v24, v24 quad_perm:[1,0,3,2] row_mask:0xf bank_mask:0xf
	v_mov_b32_e32 v20, v17
	s_nop 1
	v_add_f32_dpp v24, v24, v24 quad_perm:[2,3,0,1] row_mask:0xf bank_mask:0xf
	s_nop 1
	v_add_f32_dpp v24, v24, v24 row_half_mirror row_mask:0xf bank_mask:0xf
	s_nop 1
	v_add_f32_dpp v24, v24, v24 row_mirror row_mask:0xf bank_mask:0xf
	v_fmamk_f32 v24, v24, 0x3c000000, v177
	v_rsq_f32_e32 v26, v24
	v_mov_b32_e32 v24, v29
	v_pk_mul_f32 v[56:57], v[26:27], v[72:73] op_sel_hi:[0,1]
	v_pk_mul_f32 v[56:57], v[74:75], v[56:57]
	v_pk_mul_f32 v[54:55], v[26:27], v[54:55] op_sel_hi:[0,1]
	v_pk_mul_f32 v[70:71], v[70:71], v[56:57]
	v_pk_mul_f32 v[56:57], v[76:77], v[56:57]
	v_sub_f32_e32 v16, v71, v70
	v_mul_f32_e32 v30, v67, v16
	v_add_f32_e32 v16, v56, v57
	v_mul_f32_e32 v56, v67, v16
	v_pk_mul_f32 v[24:25], v[24:25], v[54:55]
	v_mov_b32_e32 v16, v21
	v_pk_mul_f32 v[28:29], v[16:17], v[24:25]
	s_nop 0
	v_sub_f32_e32 v16, v29, v28
	v_mul_f32_e32 v28, v67, v16
	v_pk_mul_f32 v[16:17], v[20:21], v[24:25]
	v_mov_b32_e32 v20, v22
	v_add_f32_e32 v16, v16, v17
	v_mul_f32_e32 v24, v67, v16
	v_pk_mul_f32 v[16:17], v[26:27], v[58:59] op_sel_hi:[0,1]
	v_pk_mul_f32 v[16:17], v[60:61], v[16:17]
	v_mov_b32_e32 v21, v18
	v_pk_mul_f32 v[20:21], v[20:21], v[16:17]
	v_pk_mul_f32 v[16:17], v[62:63], v[16:17]
	v_sub_f32_e32 v18, v21, v20
	v_add_f32_e32 v16, v16, v17
	v_mul_f32_e32 v29, v67, v16
	v_pk_mul_f32 v[16:17], v[26:27], v[68:69] op_sel_hi:[0,1]
	v_mov_b32_e32 v26, v31
	v_mul_f32_e32 v25, v67, v18
	v_pk_mul_f32 v[16:17], v[26:27], v[16:17]
	v_mov_b32_e32 v18, v23
	v_mov_b32_e32 v22, v19
	v_pk_mul_f32 v[20:21], v[18:19], v[16:17]
	v_pk_mul_f32 v[16:17], v[22:23], v[16:17]
	v_sub_f32_e32 v18, v21, v20
	v_add_f32_e32 v16, v16, v17
	v_mul_f32_e32 v18, v67, v18
	v_mul_f32_e32 v19, v67, v16
	v_cvt_pk_bf16_f32 v16, v30, v28
	v_cvt_pk_bf16_f32 v17, v25, v18
	v_cvt_pk_bf16_f32 v18, v56, v24
	v_cvt_pk_bf16_f32 v19, v29, v19
	global_store_dwordx2 v[52:53], v[16:17], off
	global_store_dwordx2 v[52:53], v[18:19], off offset:128
	v_mov_b32_e32 v16, v96
	v_mov_b32_e32 v17, v97
	v_mov_b32_e32 v18, v98
	v_mov_b32_e32 v19, v99
	s_nop 0
	v_mov_b32_e32 v20, v100
	v_mov_b32_e32 v21, v101
	v_mov_b32_e32 v22, v102
	v_mov_b32_e32 v23, v103
	v_lshlrev_b32_e32 v24, 16, v51
	v_and_b32_e32 v30, 0xffff0000, v51
	v_lshlrev_b32_e32 v25, 16, v49
	v_and_b32_e32 v31, 0xffff0000, v49
	v_mov_b32_e32 v54, v24
	v_mov_b32_e32 v55, v30
	v_mov_b32_e32 v52, v25
	v_mov_b32_e32 v53, v31
; __global__ void __launch_bounds__(512, 2) fwd_mega(Args args) {
;     ...
;             int idx0 = gw;
;             for (; idx0 + 3 * NGW < TOK * 4; idx0 += 4 * NGW) {
;                 PREP_LOAD(0, idx0); PREP_LOAD(1, idx0 + NGW); PREP_LOAD(2, idx0 + 2 * NGW); PREP_LOAD(3, idx0 + 3 * NGW);
;                 PREP_ONE(p0, a0, b0, cs0, sn0, hh0); PREP_ONE(p1, a1, b1, cs1, sn1, hh1); PREP_ONE(p2, a2, b2, cs2, sn2, hh2); PREP_ONE(p3, a3, b3, cs3, sn3, hh3);
	v_pk_mul_f32 v[54:55], v[54:55], v[54:55]
	v_and_b32_e32 v49, 0xffff0000, v48
	v_pk_fma_f32 v[52:53], v[52:53], v[52:53], v[54:55]
	v_lshlrev_b32_e32 v55, 16, v48
	v_lshlrev_b32_e32 v54, 16, v50
	v_and_b32_e32 v48, 0xffff0000, v50
	v_mov_b32_e32 v60, v54
	v_mov_b32_e32 v61, v48
	v_mov_b32_e32 v50, v55
	v_mov_b32_e32 v51, v49
	v_pk_mul_f32 v[60:61], v[60:61], v[60:61]
	v_mov_b32_e32 v58, v8
	v_pk_fma_f32 v[50:51], v[50:51], v[50:51], v[60:61]
	v_mov_b32_e32 v59, v12
	v_mov_b32_e32 v28, v10
	v_mov_b32_e32 v29, v14
	v_mov_b32_e32 v57, v16
	v_add_f32_e32 v16, v50, v51
	v_add_f32_e32 v16, v16, v52
	v_add_f32_e32 v16, v16, v53
	v_mov_b32_e32 v27, v18
	v_mov_b32_e32 v56, v20
	v_mov_b32_e32 v52, v12
	v_mov_b32_e32 v53, v8
	v_mov_b32_e32 v26, v22
	s_nop 1
	v_add_f32_dpp v16, v16, v16 quad_perm:[1,0,3,2] row_mask:0xf bank_mask:0xf
	v_mov_b32_e32 v12, v9
	s_nop 1
	v_add_f32_dpp v16, v16, v16 quad_perm:[2,3,0,1] row_mask:0xf bank_mask:0xf
	s_nop 1
	v_add_f32_dpp v16, v16, v16 row_half_mirror row_mask:0xf bank_mask:0xf
	s_nop 1
	v_add_f32_dpp v16, v16, v16 row_mirror row_mask:0xf bank_mask:0xf
	v_fmamk_f32 v16, v16, 0x3c000000, v177
	v_rsq_f32_e32 v18, v16
	v_mov_b32_e32 v16, v21
	v_pk_mul_f32 v[50:51], v[18:19], v[54:55] op_sel_hi:[0,1]
	v_pk_mul_f32 v[50:51], v[56:57], v[50:51]
	v_pk_mul_f32 v[48:49], v[18:19], v[48:49] op_sel_hi:[0,1]
	v_pk_mul_f32 v[52:53], v[52:53], v[50:51]
	v_pk_mul_f32 v[50:51], v[58:59], v[50:51]
	v_sub_f32_e32 v8, v53, v52
	v_mul_f32_e32 v22, v67, v8
	v_add_f32_e32 v8, v50, v51
	v_mul_f32_e32 v50, v67, v8
	v_pk_mul_f32 v[16:17], v[16:17], v[48:49]
	v_mov_b32_e32 v8, v13
	v_pk_mul_f32 v[20:21], v[8:9], v[16:17]
	s_nop 0
	v_sub_f32_e32 v8, v21, v20
	v_mul_f32_e32 v20, v67, v8
	v_pk_mul_f32 v[8:9], v[12:13], v[16:17]
	v_mov_b32_e32 v12, v14
	v_add_f32_e32 v8, v8, v9
	v_mul_f32_e32 v16, v67, v8
	v_pk_mul_f32 v[8:9], v[18:19], v[24:25] op_sel_hi:[0,1]
	v_pk_mul_f32 v[8:9], v[26:27], v[8:9]
	v_mov_b32_e32 v13, v10
	v_pk_mul_f32 v[12:13], v[12:13], v[8:9]
	v_pk_mul_f32 v[8:9], v[28:29], v[8:9]
	v_sub_f32_e32 v10, v13, v12
	v_add_f32_e32 v8, v8, v9
	v_mul_f32_e32 v21, v67, v8
	v_pk_mul_f32 v[8:9], v[18:19], v[30:31] op_sel_hi:[0,1]
	v_mov_b32_e32 v18, v23
	v_mul_f32_e32 v17, v67, v10
	v_pk_mul_f32 v[8:9], v[18:19], v[8:9]
	v_mov_b32_e32 v10, v15
	v_mov_b32_e32 v14, v11
	v_pk_mul_f32 v[12:13], v[10:11], v[8:9]
	v_pk_mul_f32 v[8:9], v[14:15], v[8:9]
	v_sub_f32_e32 v10, v13, v12
	v_add_f32_e32 v8, v8, v9
	v_mul_f32_e32 v10, v67, v10
	v_mul_f32_e32 v11, v67, v8
	v_cvt_pk_bf16_f32 v8, v22, v20
	v_cvt_pk_bf16_f32 v9, v17, v10
	v_cvt_pk_bf16_f32 v10, v50, v16
	v_cvt_pk_bf16_f32 v11, v21, v11
	global_store_dwordx2 v[46:47], v[8:9], off
	global_store_dwordx2 v[46:47], v[10:11], off offset:128
	v_mov_b32_e32 v8, v96
	v_mov_b32_e32 v9, v97
	v_mov_b32_e32 v10, v98
	v_mov_b32_e32 v11, v99
	s_nop 0
	v_mov_b32_e32 v12, v100
	v_mov_b32_e32 v13, v101
	v_mov_b32_e32 v14, v102
	v_mov_b32_e32 v15, v103
	v_lshlrev_b32_e32 v16, 16, v45
	v_and_b32_e32 v22, 0xffff0000, v45
	v_lshlrev_b32_e32 v17, 16, v43
	v_and_b32_e32 v23, 0xffff0000, v43
	v_mov_b32_e32 v26, v16
	v_mov_b32_e32 v27, v22
	v_mov_b32_e32 v24, v17
	v_mov_b32_e32 v25, v23
	v_pk_mul_f32 v[26:27], v[26:27], v[26:27]
	v_and_b32_e32 v43, 0xffff0000, v42
	v_pk_fma_f32 v[24:25], v[24:25], v[24:25], v[26:27]
	v_lshlrev_b32_e32 v27, 16, v42
	v_lshlrev_b32_e32 v26, 16, v44
	v_and_b32_e32 v42, 0xffff0000, v44
	v_mov_b32_e32 v46, v26
	v_mov_b32_e32 v47, v42
	v_mov_b32_e32 v44, v27
	v_mov_b32_e32 v45, v43
	v_pk_mul_f32 v[46:47], v[46:47], v[46:47]
	v_mov_b32_e32 v30, v0
	v_pk_fma_f32 v[44:45], v[44:45], v[44:45], v[46:47]
	v_mov_b32_e32 v31, v4
	v_mov_b32_e32 v20, v2
	v_mov_b32_e32 v21, v6
	v_mov_b32_e32 v29, v8
	v_add_f32_e32 v8, v44, v45
	v_add_f32_e32 v8, v8, v24
	v_add_f32_e32 v8, v8, v25
	v_mov_b32_e32 v19, v10
	v_mov_b32_e32 v28, v12
	v_mov_b32_e32 v18, v14
	s_nop 1
	v_add_f32_dpp v8, v8, v8 quad_perm:[1,0,3,2] row_mask:0xf bank_mask:0xf
	s_nop 1
	v_add_f32_dpp v8, v8, v8 quad_perm:[2,3,0,1] row_mask:0xf bank_mask:0xf
	s_nop 1
	v_add_f32_dpp v8, v8, v8 row_half_mirror row_mask:0xf bank_mask:0xf
	s_nop 1
	v_add_f32_dpp v8, v8, v8 row_mirror row_mask:0xf bank_mask:0xf
	v_fmamk_f32 v8, v8, 0x3c000000, v177
	v_rsq_f32_e32 v10, v8
	v_mov_b32_e32 v8, v13
	v_pk_mul_f32 v[24:25], v[10:11], v[26:27] op_sel_hi:[0,1]
	v_pk_mul_f32 v[24:25], v[28:29], v[24:25]
	v_mov_b32_e32 v26, v4
	v_mov_b32_e32 v27, v0
	v_pk_mul_f32 v[26:27], v[26:27], v[24:25]
	v_pk_mul_f32 v[24:25], v[30:31], v[24:25]
	v_sub_f32_e32 v0, v27, v26
	v_mul_f32_e32 v14, v67, v0
	v_add_f32_e32 v0, v24, v25
	v_pk_mul_f32 v[24:25], v[10:11], v[42:43] op_sel_hi:[0,1]
	v_mul_f32_e32 v26, v67, v0
	v_pk_mul_f32 v[8:9], v[8:9], v[24:25]
	v_mov_b32_e32 v0, v5
	v_pk_mul_f32 v[12:13], v[0:1], v[8:9]
	v_mov_b32_e32 v4, v1
	v_sub_f32_e32 v0, v13, v12
	v_mul_f32_e32 v12, v67, v0
	v_pk_mul_f32 v[0:1], v[4:5], v[8:9]
	v_mov_b32_e32 v4, v6
	v_add_f32_e32 v0, v0, v1
	v_mul_f32_e32 v8, v67, v0
	v_pk_mul_f32 v[0:1], v[10:11], v[16:17] op_sel_hi:[0,1]
	v_pk_mul_f32 v[0:1], v[18:19], v[0:1]
	v_mov_b32_e32 v5, v2
	v_pk_mul_f32 v[4:5], v[4:5], v[0:1]
	v_pk_mul_f32 v[0:1], v[20:21], v[0:1]
	v_sub_f32_e32 v2, v5, v4
	v_add_f32_e32 v0, v0, v1
	v_mul_f32_e32 v13, v67, v0
	v_pk_mul_f32 v[0:1], v[10:11], v[22:23] op_sel_hi:[0,1]
	v_mov_b32_e32 v10, v15
	v_mul_f32_e32 v9, v67, v2
	v_pk_mul_f32 v[0:1], v[10:11], v[0:1]
	v_mov_b32_e32 v2, v7
	v_mov_b32_e32 v6, v3
	v_pk_mul_f32 v[4:5], v[2:3], v[0:1]
	v_pk_mul_f32 v[0:1], v[6:7], v[0:1]
	v_sub_f32_e32 v2, v5, v4
	v_add_f32_e32 v0, v0, v1
	v_mul_f32_e32 v2, v67, v2
	v_mul_f32_e32 v3, v67, v0
	v_cvt_pk_bf16_f32 v0, v14, v12
	v_cvt_pk_bf16_f32 v1, v9, v2
	v_cvt_pk_bf16_f32 v2, v26, v8
	v_cvt_pk_bf16_f32 v3, v13, v3
	global_store_dwordx2 v[40:41], v[0:1], off
	global_store_dwordx2 v[40:41], v[2:3], off offset:128
	s_cbranch_scc0 .LBB0_137
